# prologue de-serialisation: each weight-conversion item issues its 32 row loads at once (counted vmcnt retire) instead of 4 dependent batches of 8
# baseline (speedup 1.0000x reference)
.LBB0_35:
	v_lshl_add_u64 v[36:37], v[34:35], 0, s[30:31]
	v_lshl_add_u64 v[38:39], v[32:33], 0, s[30:31]
	v_lshl_add_u64 v[40:41], v[30:31], 0, s[30:31]
	v_lshl_add_u64 v[42:43], v[28:29], 0, s[30:31]
	v_lshl_add_u64 v[54:55], v[6:7], 0, s[30:31]
	v_lshl_add_u64 v[56:57], v[4:5], 0, s[30:31]
	v_lshl_add_u64 v[58:59], v[2:3], 0, s[30:31]
	v_lshl_add_u64 v[60:61], v[0:1], 0, s[30:31]
	global_load_dword v70, v[36:37], off nt
	global_load_dword v71, v[38:39], off nt
	global_load_dword v72, v[40:41], off nt
	global_load_dword v73, v[42:43], off nt
	global_load_dword v74, v[54:55], off nt
	global_load_dword v75, v[56:57], off nt
	global_load_dword v76, v[58:59], off nt
	global_load_dword v77, v[60:61], off nt
	s_add_u32 s30, s30, 0x20000
	s_addc_u32 s31, s31, 0
	v_lshl_add_u64 v[36:37], v[34:35], 0, s[30:31]
	v_lshl_add_u64 v[38:39], v[32:33], 0, s[30:31]
	v_lshl_add_u64 v[40:41], v[30:31], 0, s[30:31]
	v_lshl_add_u64 v[42:43], v[28:29], 0, s[30:31]
	v_lshl_add_u64 v[54:55], v[6:7], 0, s[30:31]
	v_lshl_add_u64 v[56:57], v[4:5], 0, s[30:31]
	v_lshl_add_u64 v[58:59], v[2:3], 0, s[30:31]
	v_lshl_add_u64 v[60:61], v[0:1], 0, s[30:31]
	global_load_dword v78, v[36:37], off nt
	global_load_dword v79, v[38:39], off nt
	global_load_dword v80, v[40:41], off nt
	global_load_dword v81, v[42:43], off nt
	global_load_dword v82, v[54:55], off nt
	global_load_dword v83, v[56:57], off nt
	global_load_dword v84, v[58:59], off nt
	global_load_dword v85, v[60:61], off nt
	s_add_u32 s30, s30, 0x20000
	s_addc_u32 s31, s31, 0
	v_lshl_add_u64 v[36:37], v[34:35], 0, s[30:31]
	v_lshl_add_u64 v[38:39], v[32:33], 0, s[30:31]
	v_lshl_add_u64 v[40:41], v[30:31], 0, s[30:31]
	v_lshl_add_u64 v[42:43], v[28:29], 0, s[30:31]
	v_lshl_add_u64 v[54:55], v[6:7], 0, s[30:31]
	v_lshl_add_u64 v[56:57], v[4:5], 0, s[30:31]
	v_lshl_add_u64 v[58:59], v[2:3], 0, s[30:31]
	v_lshl_add_u64 v[60:61], v[0:1], 0, s[30:31]
	global_load_dword v86, v[36:37], off nt
	global_load_dword v87, v[38:39], off nt
	global_load_dword v88, v[40:41], off nt
	global_load_dword v89, v[42:43], off nt
	global_load_dword v90, v[54:55], off nt
	global_load_dword v91, v[56:57], off nt
	global_load_dword v92, v[58:59], off nt
	global_load_dword v93, v[60:61], off nt
	s_add_u32 s30, s30, 0x20000
	s_addc_u32 s31, s31, 0
	v_lshl_add_u64 v[36:37], v[34:35], 0, s[30:31]
	v_lshl_add_u64 v[38:39], v[32:33], 0, s[30:31]
	v_lshl_add_u64 v[40:41], v[30:31], 0, s[30:31]
	v_lshl_add_u64 v[42:43], v[28:29], 0, s[30:31]
	v_lshl_add_u64 v[54:55], v[6:7], 0, s[30:31]
	v_lshl_add_u64 v[56:57], v[4:5], 0, s[30:31]
	v_lshl_add_u64 v[58:59], v[2:3], 0, s[30:31]
	v_lshl_add_u64 v[60:61], v[0:1], 0, s[30:31]
	global_load_dword v94, v[36:37], off nt
	global_load_dword v95, v[38:39], off nt
	global_load_dword v96, v[40:41], off nt
	global_load_dword v97, v[42:43], off nt
	global_load_dword v98, v[54:55], off nt
	global_load_dword v99, v[56:57], off nt
	global_load_dword v100, v[58:59], off nt
	global_load_dword v101, v[60:61], off nt
	s_add_u32 s30, s30, 0x20000
	s_addc_u32 s31, s31, 0
	v_add_u32_e32 v54, 0x400, v14
	s_waitcnt vmcnt(30)
	ds_write2_b32 v14, v70, v71 offset1:66
	s_waitcnt vmcnt(28)
	ds_write2_b32 v14, v72, v73 offset0:132 offset1:198
	s_waitcnt vmcnt(26)
	ds_write2_b32 v54, v74, v75 offset0:8 offset1:74
	s_waitcnt vmcnt(24)
	ds_write2_b32 v54, v76, v77 offset0:140 offset1:206
	v_add_u32_e32 v14, 0x840, v14
	v_add_u32_e32 v54, 0x400, v14
	s_waitcnt vmcnt(22)
	ds_write2_b32 v14, v78, v79 offset1:66
	s_waitcnt vmcnt(20)
	ds_write2_b32 v14, v80, v81 offset0:132 offset1:198
	s_waitcnt vmcnt(18)
	ds_write2_b32 v54, v82, v83 offset0:8 offset1:74
	s_waitcnt vmcnt(16)
	ds_write2_b32 v54, v84, v85 offset0:140 offset1:206
	v_add_u32_e32 v14, 0x840, v14
	v_add_u32_e32 v54, 0x400, v14
	s_waitcnt vmcnt(14)
	ds_write2_b32 v14, v86, v87 offset1:66
	s_waitcnt vmcnt(12)
	ds_write2_b32 v14, v88, v89 offset0:132 offset1:198
	s_waitcnt vmcnt(10)
	ds_write2_b32 v54, v90, v91 offset0:8 offset1:74
	s_waitcnt vmcnt(8)
	ds_write2_b32 v54, v92, v93 offset0:140 offset1:206
	v_add_u32_e32 v14, 0x840, v14
	v_add_u32_e32 v54, 0x400, v14
	s_waitcnt vmcnt(6)
	ds_write2_b32 v14, v94, v95 offset1:66
	s_waitcnt vmcnt(4)
	ds_write2_b32 v14, v96, v97 offset0:132 offset1:198
	s_waitcnt vmcnt(2)
	ds_write2_b32 v54, v98, v99 offset0:8 offset1:74
	s_waitcnt vmcnt(0)
	ds_write2_b32 v54, v100, v101 offset0:140 offset1:206
	v_add_u32_e32 v14, 0x840, v14
	s_cmp_lg_u32 s30, 0x80000
	s_waitcnt lgkmcnt(0)
	ds_read2_b32 v[4:5], v11 offset1:8
	ds_read2_b32 v[28:29], v11 offset0:33 offset1:41
	ds_read2_b32 v[30:31], v11 offset0:66 offset1:74
	ds_read2_b32 v[32:33], v11 offset0:99 offset1:107
	s_lshl_b32 s30, s56, 5
	s_waitcnt lgkmcnt(3)
	v_bfe_u32 v0, v4, 16, 1
	s_and_b32 s35, s30, 0x7e0
	v_add3_u32 v0, v4, v0, s52
	s_waitcnt lgkmcnt(2)
	v_bfe_u32 v1, v28, 16, 1
	ds_read2_b32 v[34:35], v11 offset0:132 offset1:140
	s_and_b64 s[30:31], s[12:13], exec
	v_lshrrev_b32_e32 v0, 16, v0
	v_add3_u32 v1, v28, v1, s52
	ds_read2_b32 v[36:37], v11 offset0:165 offset1:173
	s_cselect_b32 s30, 0x800000, 0
	s_and_b64 s[28:29], s[28:29], exec
	v_and_or_b32 v0, v1, s53, v0
	s_waitcnt lgkmcnt(3)
	v_bfe_u32 v1, v30, 16, 1
	s_cselect_b32 s28, s51, 0x23600000
	v_add3_u32 v1, v30, v1, s52
	s_waitcnt lgkmcnt(2)
	v_bfe_u32 v2, v32, 16, 1
	ds_read2_b32 v[38:39], v11 offset0:198 offset1:206
	s_add_u32 s28, s88, s28
	v_lshrrev_b32_e32 v1, 16, v1
	v_add3_u32 v2, v32, v2, s52
	ds_read2_b32 v[40:41], v11 offset0:231 offset1:239
	s_addc_u32 s29, s89, 0
	v_and_or_b32 v1, v2, s53, v1
	s_waitcnt lgkmcnt(3)
	v_bfe_u32 v2, v34, 16, 1
	s_add_u32 s28, s28, s30
	v_add3_u32 v2, v34, v2, s52
	s_waitcnt lgkmcnt(2)
	v_bfe_u32 v3, v36, 16, 1
	s_addc_u32 s29, s29, 0
	s_lshl_b32 s30, s34, 1
	v_lshrrev_b32_e32 v2, 16, v2
	v_add3_u32 v3, v36, v3, s52
	s_add_u32 s28, s28, s30
	v_and_or_b32 v2, v3, s53, v2
	s_waitcnt lgkmcnt(1)
	v_bfe_u32 v3, v38, 16, 1
	v_add_u32_e32 v42, s35, v9
	s_addc_u32 s29, s29, 0
	v_lshlrev_b32_e32 v14, 1, v12
	v_add3_u32 v3, v38, v3, s52
	s_waitcnt lgkmcnt(0)
	v_bfe_u32 v4, v40, 16, 1
	v_ashrrev_i32_e32 v43, 31, v42
	v_lshl_add_u64 v[6:7], s[28:29], 0, v[14:15]
	v_lshrrev_b32_e32 v3, 16, v3
	v_add3_u32 v4, v40, v4, s52
	v_lshlrev_b64 v[42:43], 12, v[42:43]
	v_and_or_b32 v3, v4, s53, v3
	v_lshl_add_u64 v[42:43], v[6:7], 0, v[42:43]
	global_store_dwordx4 v[42:43], v[0:3], off nt
	v_bfe_u32 v4, v41, 16, 1
	v_add3_u32 v4, v41, v4, s52
	v_bfe_u32 v0, v5, 16, 1
	v_add3_u32 v0, v5, v0, s52
	v_bfe_u32 v1, v29, 16, 1
	v_lshrrev_b32_e32 v0, 16, v0
	v_add3_u32 v1, v29, v1, s52
	v_and_or_b32 v0, v1, s53, v0
	v_bfe_u32 v1, v31, 16, 1
	v_add3_u32 v1, v31, v1, s52
	v_bfe_u32 v2, v33, 16, 1
	v_lshrrev_b32_e32 v1, 16, v1
	v_add3_u32 v2, v33, v2, s52
	v_and_or_b32 v1, v2, s53, v1
	v_bfe_u32 v2, v35, 16, 1
	v_add3_u32 v2, v35, v2, s52
	v_bfe_u32 v3, v37, 16, 1
	v_lshrrev_b32_e32 v2, 16, v2
	v_add3_u32 v3, v37, v3, s52
	v_and_or_b32 v2, v3, s53, v2
	v_bfe_u32 v3, v39, 16, 1
	v_add3_u32 v3, v39, v3, s52
	v_lshrrev_b32_e32 v3, 16, v3
	v_and_or_b32 v3, v4, s53, v3
	v_add_u32_e32 v4, s35, v13
	v_ashrrev_i32_e32 v5, 31, v4
	v_lshlrev_b64 v[4:5], 12, v[4:5]
	ds_read2_b32 v[28:29], v11 offset0:16 offset1:24
	v_lshl_add_u64 v[4:5], v[6:7], 0, v[4:5]
	global_store_dwordx4 v[4:5], v[0:3], off nt
	ds_read2_b32 v[4:5], v11 offset0:49 offset1:57
	ds_read2_b32 v[30:31], v11 offset0:82 offset1:90
	ds_read2_b32 v[32:33], v11 offset0:115 offset1:123
	s_waitcnt lgkmcnt(3)
	v_bfe_u32 v0, v28, 16, 1
	v_add3_u32 v0, v28, v0, s52
	s_waitcnt lgkmcnt(2)
	v_bfe_u32 v1, v4, 16, 1
	ds_read2_b32 v[34:35], v11 offset0:148 offset1:156
	v_lshrrev_b32_e32 v0, 16, v0
	v_add3_u32 v1, v4, v1, s52
	ds_read2_b32 v[36:37], v11 offset0:181 offset1:189
	v_and_or_b32 v0, v1, s53, v0
	s_waitcnt lgkmcnt(3)
	v_bfe_u32 v1, v30, 16, 1
	v_add3_u32 v1, v30, v1, s52
	s_waitcnt lgkmcnt(2)
	v_bfe_u32 v2, v32, 16, 1
	ds_read2_b32 v[38:39], v11 offset0:214 offset1:222
	v_lshrrev_b32_e32 v1, 16, v1
	v_add3_u32 v2, v32, v2, s52
	ds_read2_b32 v[40:41], v11 offset0:247 offset1:255
	v_and_or_b32 v1, v2, s53, v1
	s_waitcnt lgkmcnt(3)
	v_bfe_u32 v2, v34, 16, 1
	v_add3_u32 v2, v34, v2, s52
	s_waitcnt lgkmcnt(2)
	v_bfe_u32 v3, v36, 16, 1
	v_lshrrev_b32_e32 v2, 16, v2
	v_add3_u32 v3, v36, v3, s52
	v_and_or_b32 v2, v3, s53, v2
	s_waitcnt lgkmcnt(1)
	v_bfe_u32 v3, v38, 16, 1
	v_add_u32_e32 v42, s35, v44
	v_add3_u32 v3, v38, v3, s52
	s_waitcnt lgkmcnt(0)
	v_bfe_u32 v4, v40, 16, 1
	v_ashrrev_i32_e32 v43, 31, v42
	v_lshrrev_b32_e32 v3, 16, v3
	v_add3_u32 v4, v40, v4, s52
	v_lshlrev_b64 v[42:43], 12, v[42:43]
	v_and_or_b32 v3, v4, s53, v3
	v_lshl_add_u64 v[42:43], v[6:7], 0, v[42:43]
	global_store_dwordx4 v[42:43], v[0:3], off nt
	v_bfe_u32 v4, v41, 16, 1
	v_add3_u32 v4, v41, v4, s52
	v_bfe_u32 v0, v29, 16, 1
	v_add3_u32 v0, v29, v0, s52
	v_bfe_u32 v1, v5, 16, 1
	v_lshrrev_b32_e32 v0, 16, v0
	v_add3_u32 v1, v5, v1, s52
	v_and_or_b32 v0, v1, s53, v0
	v_bfe_u32 v1, v31, 16, 1
	v_add3_u32 v1, v31, v1, s52
	v_bfe_u32 v2, v33, 16, 1
	v_lshrrev_b32_e32 v1, 16, v1
	v_add3_u32 v2, v33, v2, s52
	v_and_or_b32 v1, v2, s53, v1
	v_bfe_u32 v2, v35, 16, 1
	v_add3_u32 v2, v35, v2, s52
	v_bfe_u32 v3, v37, 16, 1
	v_lshrrev_b32_e32 v2, 16, v2
	v_add3_u32 v3, v37, v3, s52
	v_and_or_b32 v2, v3, s53, v2
	v_bfe_u32 v3, v39, 16, 1
	v_add3_u32 v3, v39, v3, s52
	v_lshrrev_b32_e32 v3, 16, v3
	v_and_or_b32 v3, v4, s53, v3
	v_add_u32_e32 v4, s35, v45
	v_ashrrev_i32_e32 v5, 31, v4
	v_lshlrev_b64 v[4:5], 12, v[4:5]
	v_lshl_add_u64 v[4:5], v[6:7], 0, v[4:5]
	global_store_dwordx4 v[4:5], v[0:3], off nt
	s_waitcnt lgkmcnt(0)
	s_mov_b64 s[30:31], 0

.LBB0_40:
	v_lshl_add_u64 v[54:55], v[42:43], 0, s[16:17]
	v_lshl_add_u64 v[56:57], v[40:41], 0, s[16:17]
	v_lshl_add_u64 v[58:59], v[38:39], 0, s[16:17]
	v_lshl_add_u64 v[60:61], v[36:37], 0, s[16:17]
	v_lshl_add_u64 v[62:63], v[34:35], 0, s[16:17]
	v_lshl_add_u64 v[64:65], v[32:33], 0, s[16:17]
	v_lshl_add_u64 v[66:67], v[30:31], 0, s[16:17]
	v_lshl_add_u64 v[68:69], v[28:29], 0, s[16:17]
	global_load_dword v70, v[54:55], off nt
	global_load_dword v71, v[56:57], off nt
	global_load_dword v72, v[58:59], off nt
	global_load_dword v73, v[60:61], off nt
	global_load_dword v74, v[62:63], off nt
	global_load_dword v75, v[64:65], off nt
	global_load_dword v76, v[66:67], off nt
	global_load_dword v77, v[68:69], off nt
	s_add_u32 s16, s16, 0x48000
	s_addc_u32 s17, s17, 0
	v_lshl_add_u64 v[54:55], v[42:43], 0, s[16:17]
	v_lshl_add_u64 v[56:57], v[40:41], 0, s[16:17]
	v_lshl_add_u64 v[58:59], v[38:39], 0, s[16:17]
	v_lshl_add_u64 v[60:61], v[36:37], 0, s[16:17]
	v_lshl_add_u64 v[62:63], v[34:35], 0, s[16:17]
	v_lshl_add_u64 v[64:65], v[32:33], 0, s[16:17]
	v_lshl_add_u64 v[66:67], v[30:31], 0, s[16:17]
	v_lshl_add_u64 v[68:69], v[28:29], 0, s[16:17]
	global_load_dword v78, v[54:55], off nt
	global_load_dword v79, v[56:57], off nt
	global_load_dword v80, v[58:59], off nt
	global_load_dword v81, v[60:61], off nt
	global_load_dword v82, v[62:63], off nt
	global_load_dword v83, v[64:65], off nt
	global_load_dword v84, v[66:67], off nt
	global_load_dword v85, v[68:69], off nt
	s_add_u32 s16, s16, 0x48000
	s_addc_u32 s17, s17, 0
	v_lshl_add_u64 v[54:55], v[42:43], 0, s[16:17]
	v_lshl_add_u64 v[56:57], v[40:41], 0, s[16:17]
	v_lshl_add_u64 v[58:59], v[38:39], 0, s[16:17]
	v_lshl_add_u64 v[60:61], v[36:37], 0, s[16:17]
	v_lshl_add_u64 v[62:63], v[34:35], 0, s[16:17]
	v_lshl_add_u64 v[64:65], v[32:33], 0, s[16:17]
	v_lshl_add_u64 v[66:67], v[30:31], 0, s[16:17]
	v_lshl_add_u64 v[68:69], v[28:29], 0, s[16:17]
	global_load_dword v86, v[54:55], off nt
	global_load_dword v87, v[56:57], off nt
	global_load_dword v88, v[58:59], off nt
	global_load_dword v89, v[60:61], off nt
	global_load_dword v90, v[62:63], off nt
	global_load_dword v91, v[64:65], off nt
	global_load_dword v92, v[66:67], off nt
	global_load_dword v93, v[68:69], off nt
	s_add_u32 s16, s16, 0x48000
	s_addc_u32 s17, s17, 0
	v_lshl_add_u64 v[54:55], v[42:43], 0, s[16:17]
	v_lshl_add_u64 v[56:57], v[40:41], 0, s[16:17]
	v_lshl_add_u64 v[58:59], v[38:39], 0, s[16:17]
	v_lshl_add_u64 v[60:61], v[36:37], 0, s[16:17]
	v_lshl_add_u64 v[62:63], v[34:35], 0, s[16:17]
	v_lshl_add_u64 v[64:65], v[32:33], 0, s[16:17]
	v_lshl_add_u64 v[66:67], v[30:31], 0, s[16:17]
	v_lshl_add_u64 v[68:69], v[28:29], 0, s[16:17]
	global_load_dword v94, v[54:55], off nt
	global_load_dword v95, v[56:57], off nt
	global_load_dword v96, v[58:59], off nt
	global_load_dword v97, v[60:61], off nt
	global_load_dword v98, v[62:63], off nt
	global_load_dword v99, v[64:65], off nt
	global_load_dword v100, v[66:67], off nt
	global_load_dword v101, v[68:69], off nt
	s_add_u32 s16, s16, 0x48000
	s_addc_u32 s17, s17, 0
	v_add_u32_e32 v62, 0x400, v14
	s_waitcnt vmcnt(30)
	ds_write2_b32 v14, v70, v71 offset1:66
	s_waitcnt vmcnt(28)
	ds_write2_b32 v14, v72, v73 offset0:132 offset1:198
	s_waitcnt vmcnt(26)
	ds_write2_b32 v62, v74, v75 offset0:8 offset1:74
	s_waitcnt vmcnt(24)
	ds_write2_b32 v62, v76, v77 offset0:140 offset1:206
	v_add_u32_e32 v14, 0x840, v14
	v_add_u32_e32 v62, 0x400, v14
	s_waitcnt vmcnt(22)
	ds_write2_b32 v14, v78, v79 offset1:66
	s_waitcnt vmcnt(20)
	ds_write2_b32 v14, v80, v81 offset0:132 offset1:198
	s_waitcnt vmcnt(18)
	ds_write2_b32 v62, v82, v83 offset0:8 offset1:74
	s_waitcnt vmcnt(16)
	ds_write2_b32 v62, v84, v85 offset0:140 offset1:206
	v_add_u32_e32 v14, 0x840, v14
	v_add_u32_e32 v62, 0x400, v14
	s_waitcnt vmcnt(14)
	ds_write2_b32 v14, v86, v87 offset1:66
	s_waitcnt vmcnt(12)
	ds_write2_b32 v14, v88, v89 offset0:132 offset1:198
	s_waitcnt vmcnt(10)
	ds_write2_b32 v62, v90, v91 offset0:8 offset1:74
	s_waitcnt vmcnt(8)
	ds_write2_b32 v62, v92, v93 offset0:140 offset1:206
	v_add_u32_e32 v14, 0x840, v14
	v_add_u32_e32 v62, 0x400, v14
	s_waitcnt vmcnt(6)
	ds_write2_b32 v14, v94, v95 offset1:66
	s_waitcnt vmcnt(4)
	ds_write2_b32 v14, v96, v97 offset0:132 offset1:198
	s_waitcnt vmcnt(2)
	ds_write2_b32 v62, v98, v99 offset0:8 offset1:74
	s_waitcnt vmcnt(0)
	ds_write2_b32 v62, v100, v101 offset0:140 offset1:206
	v_add_u32_e32 v14, 0x840, v14
	s_cmp_lg_u32 s16, 0x120000
	s_waitcnt lgkmcnt(0)
	ds_read2_b32 v[32:33], v11 offset1:8
	ds_read2_b32 v[34:35], v11 offset0:33 offset1:41
	ds_read2_b32 v[38:39], v11 offset0:66 offset1:74
	ds_read2_b32 v[40:41], v11 offset0:99 offset1:107
	ds_read2_b32 v[42:43], v11 offset0:132 offset1:140
	ds_read2_b32 v[54:55], v11 offset0:165 offset1:173
	ds_read2_b32 v[56:57], v11 offset0:198 offset1:206
	ds_read2_b32 v[58:59], v11 offset0:231 offset1:239
	s_and_b32 s31, 0xffff, s31
	s_and_b64 s[16:17], s[12:13], exec
	s_waitcnt lgkmcnt(7)
	v_mov_b32_e32 v28, v32
	s_waitcnt lgkmcnt(6)
	v_mov_b32_e32 v29, v34
	s_waitcnt lgkmcnt(5)
	v_mov_b32_e32 v30, v38
	s_waitcnt lgkmcnt(4)
	v_mov_b32_e32 v31, v40
	s_cselect_b32 s16, 0x1200000, 0
	v_pk_mul_f32 v[28:29], v[4:5], v[28:29]
	v_pk_mul_f32 v[30:31], v[6:7], v[30:31]
	s_add_u32 s16, s2, s16
	v_cvt_pk_f16_f32 v28, v28, v29
	v_cvt_pk_f16_f32 v29, v30, v31
	s_waitcnt lgkmcnt(3)
	v_mov_b32_e32 v30, v42
	s_waitcnt lgkmcnt(2)
	v_mov_b32_e32 v31, v54
	s_waitcnt lgkmcnt(1)
	v_mov_b32_e32 v60, v56
	s_waitcnt lgkmcnt(0)
	v_mov_b32_e32 v61, v58
	s_addc_u32 s17, s3, 0
	s_lshl_b32 s30, s30, 1
	v_pk_mul_f32 v[30:31], v[0:1], v[30:31]
	v_pk_mul_f32 v[60:61], v[2:3], v[60:61]
	s_add_u32 s16, s16, s30
	v_cvt_pk_f16_f32 v30, v30, v31
	v_cvt_pk_f16_f32 v31, v60, v61
	v_add_u32_e32 v60, s31, v9
	s_addc_u32 s17, s17, 0
	v_lshlrev_b32_e32 v14, 1, v12
	v_ashrrev_i32_e32 v61, 31, v60
	v_lshl_add_u64 v[36:37], s[16:17], 0, v[14:15]
	v_lshlrev_b64 v[60:61], 12, v[60:61]
	v_lshl_add_u64 v[60:61], v[36:37], 0, v[60:61]
	v_mov_b32_e32 v34, v33
	v_mov_b32_e32 v40, v39
	global_store_dwordx4 v[60:61], v[28:31], off nt
	v_mov_b32_e32 v54, v43
	v_mov_b32_e32 v58, v57
	v_pk_mul_f32 v[28:29], v[4:5], v[34:35]
	v_pk_mul_f32 v[30:31], v[6:7], v[40:41]
	v_cvt_pk_f16_f32 v28, v28, v29
	v_cvt_pk_f16_f32 v29, v30, v31
	v_pk_mul_f32 v[30:31], v[0:1], v[54:55]
	v_pk_mul_f32 v[32:33], v[2:3], v[58:59]
	v_cvt_pk_f16_f32 v30, v30, v31
	v_cvt_pk_f16_f32 v31, v32, v33
	v_add_u32_e32 v32, s31, v13
	v_ashrrev_i32_e32 v33, 31, v32
	v_lshlrev_b64 v[32:33], 12, v[32:33]
	v_lshl_add_u64 v[32:33], v[36:37], 0, v[32:33]
	ds_read2_b32 v[34:35], v11 offset0:16 offset1:24
	ds_read2_b32 v[38:39], v11 offset0:49 offset1:57
	global_store_dwordx4 v[32:33], v[28:31], off nt
	ds_read2_b32 v[32:33], v11 offset0:82 offset1:90
	ds_read2_b32 v[40:41], v11 offset0:115 offset1:123
	ds_read2_b32 v[42:43], v11 offset0:148 offset1:156
	ds_read2_b32 v[54:55], v11 offset0:181 offset1:189
	ds_read2_b32 v[56:57], v11 offset0:214 offset1:222
	ds_read2_b32 v[58:59], v11 offset0:247 offset1:255
	s_waitcnt lgkmcnt(7)
	v_mov_b32_e32 v28, v34
	s_waitcnt lgkmcnt(6)
	v_mov_b32_e32 v29, v38
	s_waitcnt lgkmcnt(5)
	v_mov_b32_e32 v30, v32
	s_waitcnt lgkmcnt(4)
	v_mov_b32_e32 v31, v40
	v_pk_mul_f32 v[28:29], v[4:5], v[28:29]
	v_pk_mul_f32 v[30:31], v[6:7], v[30:31]
	v_cvt_pk_f16_f32 v28, v28, v29
	v_cvt_pk_f16_f32 v29, v30, v31
	s_waitcnt lgkmcnt(3)
	v_mov_b32_e32 v30, v42
	s_waitcnt lgkmcnt(2)
	v_mov_b32_e32 v31, v54
	v_mov_b32_e32 v38, v35
	v_mov_b32_e32 v40, v33
	v_mov_b32_e32 v54, v43
	v_pk_mul_f32 v[30:31], v[0:1], v[30:31]
	s_waitcnt lgkmcnt(1)
	v_mov_b32_e32 v60, v56
	s_waitcnt lgkmcnt(0)
	v_mov_b32_e32 v61, v58
	v_pk_mul_f32 v[4:5], v[4:5], v[38:39]
	v_pk_mul_f32 v[6:7], v[6:7], v[40:41]
	v_pk_mul_f32 v[0:1], v[0:1], v[54:55]
	v_mov_b32_e32 v58, v57
	v_pk_mul_f32 v[60:61], v[2:3], v[60:61]
	v_cvt_pk_f16_f32 v4, v4, v5
	v_cvt_pk_f16_f32 v5, v6, v7
	v_cvt_pk_f16_f32 v6, v0, v1
	v_pk_mul_f32 v[0:1], v[2:3], v[58:59]
	v_cvt_pk_f16_f32 v30, v30, v31
	v_cvt_pk_f16_f32 v31, v60, v61
	v_add_u32_e32 v60, s31, v44
	v_cvt_pk_f16_f32 v7, v0, v1
	v_add_u32_e32 v0, s31, v45
	v_ashrrev_i32_e32 v61, 31, v60
	v_ashrrev_i32_e32 v1, 31, v0
	v_lshlrev_b64 v[60:61], 12, v[60:61]
	v_lshlrev_b64 v[0:1], 12, v[0:1]
	v_lshl_add_u64 v[60:61], v[36:37], 0, v[60:61]
	v_lshl_add_u64 v[0:1], v[36:37], 0, v[0:1]
	global_store_dwordx4 v[60:61], v[28:31], off nt
	global_store_dwordx4 v[0:1], v[4:7], off nt
	s_waitcnt lgkmcnt(0)
	s_mov_b64 s[16:17], 0

.LBB0_44:
	v_lshl_add_u64 v[54:55], v[42:43], 0, s[16:17]
	v_lshl_add_u64 v[56:57], v[40:41], 0, s[16:17]
	v_lshl_add_u64 v[58:59], v[38:39], 0, s[16:17]
	v_lshl_add_u64 v[60:61], v[36:37], 0, s[16:17]
	v_lshl_add_u64 v[62:63], v[34:35], 0, s[16:17]
	v_lshl_add_u64 v[64:65], v[32:33], 0, s[16:17]
	v_lshl_add_u64 v[66:67], v[30:31], 0, s[16:17]
	v_lshl_add_u64 v[68:69], v[28:29], 0, s[16:17]
	global_load_dword v70, v[54:55], off nt
	global_load_dword v71, v[56:57], off nt
	global_load_dword v72, v[58:59], off nt
	global_load_dword v73, v[60:61], off nt
	global_load_dword v74, v[62:63], off nt
	global_load_dword v75, v[64:65], off nt
	global_load_dword v76, v[66:67], off nt
	global_load_dword v77, v[68:69], off nt
	s_add_u32 s16, s16, 0x60000
	s_addc_u32 s17, s17, 0
	v_lshl_add_u64 v[54:55], v[42:43], 0, s[16:17]
	v_lshl_add_u64 v[56:57], v[40:41], 0, s[16:17]
	v_lshl_add_u64 v[58:59], v[38:39], 0, s[16:17]
	v_lshl_add_u64 v[60:61], v[36:37], 0, s[16:17]
	v_lshl_add_u64 v[62:63], v[34:35], 0, s[16:17]
	v_lshl_add_u64 v[64:65], v[32:33], 0, s[16:17]
	v_lshl_add_u64 v[66:67], v[30:31], 0, s[16:17]
	v_lshl_add_u64 v[68:69], v[28:29], 0, s[16:17]
	global_load_dword v78, v[54:55], off nt
	global_load_dword v79, v[56:57], off nt
	global_load_dword v80, v[58:59], off nt
	global_load_dword v81, v[60:61], off nt
	global_load_dword v82, v[62:63], off nt
	global_load_dword v83, v[64:65], off nt
	global_load_dword v84, v[66:67], off nt
	global_load_dword v85, v[68:69], off nt
	s_add_u32 s16, s16, 0x60000
	s_addc_u32 s17, s17, 0
	v_lshl_add_u64 v[54:55], v[42:43], 0, s[16:17]
	v_lshl_add_u64 v[56:57], v[40:41], 0, s[16:17]
	v_lshl_add_u64 v[58:59], v[38:39], 0, s[16:17]
	v_lshl_add_u64 v[60:61], v[36:37], 0, s[16:17]
	v_lshl_add_u64 v[62:63], v[34:35], 0, s[16:17]
	v_lshl_add_u64 v[64:65], v[32:33], 0, s[16:17]
	v_lshl_add_u64 v[66:67], v[30:31], 0, s[16:17]
	v_lshl_add_u64 v[68:69], v[28:29], 0, s[16:17]
	global_load_dword v86, v[54:55], off nt
	global_load_dword v87, v[56:57], off nt
	global_load_dword v88, v[58:59], off nt
	global_load_dword v89, v[60:61], off nt
	global_load_dword v90, v[62:63], off nt
	global_load_dword v91, v[64:65], off nt
	global_load_dword v92, v[66:67], off nt
	global_load_dword v93, v[68:69], off nt
	s_add_u32 s16, s16, 0x60000
	s_addc_u32 s17, s17, 0
	v_lshl_add_u64 v[54:55], v[42:43], 0, s[16:17]
	v_lshl_add_u64 v[56:57], v[40:41], 0, s[16:17]
	v_lshl_add_u64 v[58:59], v[38:39], 0, s[16:17]
	v_lshl_add_u64 v[60:61], v[36:37], 0, s[16:17]
	v_lshl_add_u64 v[62:63], v[34:35], 0, s[16:17]
	v_lshl_add_u64 v[64:65], v[32:33], 0, s[16:17]
	v_lshl_add_u64 v[66:67], v[30:31], 0, s[16:17]
	v_lshl_add_u64 v[68:69], v[28:29], 0, s[16:17]
	global_load_dword v94, v[54:55], off nt
	global_load_dword v95, v[56:57], off nt
	global_load_dword v96, v[58:59], off nt
	global_load_dword v97, v[60:61], off nt
	global_load_dword v98, v[62:63], off nt
	global_load_dword v99, v[64:65], off nt
	global_load_dword v100, v[66:67], off nt
	global_load_dword v101, v[68:69], off nt
	s_add_u32 s16, s16, 0x60000
	s_addc_u32 s17, s17, 0
	v_add_u32_e32 v62, 0x400, v14
	s_waitcnt vmcnt(30)
	ds_write2_b32 v14, v70, v71 offset1:66
	s_waitcnt vmcnt(28)
	ds_write2_b32 v14, v72, v73 offset0:132 offset1:198
	s_waitcnt vmcnt(26)
	ds_write2_b32 v62, v74, v75 offset0:8 offset1:74
	s_waitcnt vmcnt(24)
	ds_write2_b32 v62, v76, v77 offset0:140 offset1:206
	v_add_u32_e32 v14, 0x840, v14
	v_add_u32_e32 v62, 0x400, v14
	s_waitcnt vmcnt(22)
	ds_write2_b32 v14, v78, v79 offset1:66
	s_waitcnt vmcnt(20)
	ds_write2_b32 v14, v80, v81 offset0:132 offset1:198
	s_waitcnt vmcnt(18)
	ds_write2_b32 v62, v82, v83 offset0:8 offset1:74
	s_waitcnt vmcnt(16)
	ds_write2_b32 v62, v84, v85 offset0:140 offset1:206
	v_add_u32_e32 v14, 0x840, v14
	v_add_u32_e32 v62, 0x400, v14
	s_waitcnt vmcnt(14)
	ds_write2_b32 v14, v86, v87 offset1:66
	s_waitcnt vmcnt(12)
	ds_write2_b32 v14, v88, v89 offset0:132 offset1:198
	s_waitcnt vmcnt(10)
	ds_write2_b32 v62, v90, v91 offset0:8 offset1:74
	s_waitcnt vmcnt(8)
	ds_write2_b32 v62, v92, v93 offset0:140 offset1:206
	v_add_u32_e32 v14, 0x840, v14
	v_add_u32_e32 v62, 0x400, v14
	s_waitcnt vmcnt(6)
	ds_write2_b32 v14, v94, v95 offset1:66
	s_waitcnt vmcnt(4)
	ds_write2_b32 v14, v96, v97 offset0:132 offset1:198
	s_waitcnt vmcnt(2)
	ds_write2_b32 v62, v98, v99 offset0:8 offset1:74
	s_waitcnt vmcnt(0)
	ds_write2_b32 v62, v100, v101 offset0:140 offset1:206
	v_add_u32_e32 v14, 0x840, v14
	s_cmp_lg_u32 s16, 0x180000
	s_waitcnt lgkmcnt(0)
	ds_read2_b32 v[32:33], v11 offset1:8
	ds_read2_b32 v[34:35], v11 offset0:33 offset1:41
	ds_read2_b32 v[38:39], v11 offset0:66 offset1:74
	ds_read2_b32 v[40:41], v11 offset0:99 offset1:107
	ds_read2_b32 v[42:43], v11 offset0:132 offset1:140
	ds_read2_b32 v[54:55], v11 offset0:165 offset1:173
	ds_read2_b32 v[56:57], v11 offset0:198 offset1:206
	ds_read2_b32 v[58:59], v11 offset0:231 offset1:239
	s_and_b32 s16, 0xffff, s31
	s_and_b64 s[12:13], s[12:13], exec
	s_waitcnt lgkmcnt(7)
	v_mov_b32_e32 v28, v32
	s_waitcnt lgkmcnt(6)
	v_mov_b32_e32 v29, v34
	s_waitcnt lgkmcnt(5)
	v_mov_b32_e32 v30, v38
	s_waitcnt lgkmcnt(4)
	v_mov_b32_e32 v31, v40
	s_cselect_b32 s12, 0x1800000, 0
	v_pk_mul_f32 v[28:29], v[4:5], v[28:29]
	v_pk_mul_f32 v[30:31], v[6:7], v[30:31]
	s_add_u32 s12, s25, s12
	v_cvt_pk_f16_f32 v28, v28, v29
	v_cvt_pk_f16_f32 v29, v30, v31
	s_waitcnt lgkmcnt(3)
	v_mov_b32_e32 v30, v42
	s_waitcnt lgkmcnt(2)
	v_mov_b32_e32 v31, v54
	s_waitcnt lgkmcnt(1)
	v_mov_b32_e32 v60, v56
	s_waitcnt lgkmcnt(0)
	v_mov_b32_e32 v61, v58
	s_addc_u32 s13, s27, 0
	s_lshl_b32 s17, s30, 1
	v_pk_mul_f32 v[30:31], v[0:1], v[30:31]
	v_pk_mul_f32 v[60:61], v[2:3], v[60:61]
	s_add_u32 s12, s12, s17
	v_cvt_pk_f16_f32 v30, v30, v31
	v_cvt_pk_f16_f32 v31, v60, v61
	v_add_u32_e32 v60, s16, v9
	s_addc_u32 s13, s13, 0
	v_lshlrev_b32_e32 v14, 1, v12
	v_ashrrev_i32_e32 v61, 31, v60
	v_lshl_add_u64 v[36:37], s[12:13], 0, v[14:15]
	v_lshlrev_b64 v[60:61], 12, v[60:61]
	v_lshl_add_u64 v[60:61], v[36:37], 0, v[60:61]
	v_mov_b32_e32 v34, v33
	v_mov_b32_e32 v40, v39
	global_store_dwordx4 v[60:61], v[28:31], off nt
	v_mov_b32_e32 v54, v43
	v_mov_b32_e32 v58, v57
	v_pk_mul_f32 v[28:29], v[4:5], v[34:35]
	v_pk_mul_f32 v[30:31], v[6:7], v[40:41]
	v_cvt_pk_f16_f32 v28, v28, v29
	v_cvt_pk_f16_f32 v29, v30, v31
	v_pk_mul_f32 v[30:31], v[0:1], v[54:55]
	v_pk_mul_f32 v[32:33], v[2:3], v[58:59]
	v_cvt_pk_f16_f32 v30, v30, v31
	v_cvt_pk_f16_f32 v31, v32, v33
	v_add_u32_e32 v32, s16, v13
	v_ashrrev_i32_e32 v33, 31, v32
	v_lshlrev_b64 v[32:33], 12, v[32:33]
	v_lshl_add_u64 v[32:33], v[36:37], 0, v[32:33]
	ds_read2_b32 v[34:35], v11 offset0:16 offset1:24
	ds_read2_b32 v[38:39], v11 offset0:49 offset1:57
	global_store_dwordx4 v[32:33], v[28:31], off nt
	ds_read2_b32 v[32:33], v11 offset0:82 offset1:90
	ds_read2_b32 v[40:41], v11 offset0:115 offset1:123
	ds_read2_b32 v[42:43], v11 offset0:148 offset1:156
	ds_read2_b32 v[54:55], v11 offset0:181 offset1:189
	ds_read2_b32 v[56:57], v11 offset0:214 offset1:222
	ds_read2_b32 v[58:59], v11 offset0:247 offset1:255
	s_waitcnt lgkmcnt(7)
	v_mov_b32_e32 v28, v34
	s_waitcnt lgkmcnt(6)
	v_mov_b32_e32 v29, v38
	s_waitcnt lgkmcnt(5)
	v_mov_b32_e32 v30, v32
	s_waitcnt lgkmcnt(4)
	v_mov_b32_e32 v31, v40
	v_pk_mul_f32 v[28:29], v[4:5], v[28:29]
	v_pk_mul_f32 v[30:31], v[6:7], v[30:31]
	v_cvt_pk_f16_f32 v28, v28, v29
	v_cvt_pk_f16_f32 v29, v30, v31
	s_waitcnt lgkmcnt(3)
	v_mov_b32_e32 v30, v42
	s_waitcnt lgkmcnt(2)
	v_mov_b32_e32 v31, v54
	v_mov_b32_e32 v38, v35
	v_mov_b32_e32 v40, v33
	v_mov_b32_e32 v54, v43
	v_pk_mul_f32 v[30:31], v[0:1], v[30:31]
	s_waitcnt lgkmcnt(1)
	v_mov_b32_e32 v60, v56
	s_waitcnt lgkmcnt(0)
	v_mov_b32_e32 v61, v58
	v_pk_mul_f32 v[4:5], v[4:5], v[38:39]
	v_pk_mul_f32 v[6:7], v[6:7], v[40:41]
	v_pk_mul_f32 v[0:1], v[0:1], v[54:55]
	v_mov_b32_e32 v58, v57
	v_pk_mul_f32 v[60:61], v[2:3], v[60:61]
	v_cvt_pk_f16_f32 v4, v4, v5
	v_cvt_pk_f16_f32 v5, v6, v7
	v_cvt_pk_f16_f32 v6, v0, v1
	v_pk_mul_f32 v[0:1], v[2:3], v[58:59]
	v_cvt_pk_f16_f32 v30, v30, v31
	v_cvt_pk_f16_f32 v31, v60, v61
	v_add_u32_e32 v60, s16, v44
	v_cvt_pk_f16_f32 v7, v0, v1
	v_add_u32_e32 v0, s16, v45
	v_ashrrev_i32_e32 v61, 31, v60
	v_ashrrev_i32_e32 v1, 31, v0
	v_lshlrev_b64 v[60:61], 12, v[60:61]
	v_lshlrev_b64 v[0:1], 12, v[0:1]
	v_lshl_add_u64 v[60:61], v[36:37], 0, v[60:61]
	v_lshl_add_u64 v[0:1], v[36:37], 0, v[0:1]
	global_store_dwordx4 v[60:61], v[28:31], off nt
	global_store_dwordx4 v[0:1], v[4:7], off nt
	s_waitcnt lgkmcnt(0)

.LBB0_49:
	v_lshl_add_u64 v[36:37], v[34:35], 0, s[12:13]
	v_lshl_add_u64 v[38:39], v[32:33], 0, s[12:13]
	v_lshl_add_u64 v[40:41], v[30:31], 0, s[12:13]
	v_lshl_add_u64 v[42:43], v[28:29], 0, s[12:13]
	v_lshl_add_u64 v[54:55], v[6:7], 0, s[12:13]
	v_lshl_add_u64 v[56:57], v[4:5], 0, s[12:13]
	v_lshl_add_u64 v[58:59], v[2:3], 0, s[12:13]
	v_lshl_add_u64 v[60:61], v[0:1], 0, s[12:13]
	global_load_dword v70, v[36:37], off nt
	global_load_dword v71, v[38:39], off nt
	global_load_dword v72, v[40:41], off nt
	global_load_dword v73, v[42:43], off nt
	global_load_dword v74, v[54:55], off nt
	global_load_dword v75, v[56:57], off nt
	global_load_dword v76, v[58:59], off nt
	global_load_dword v77, v[60:61], off nt
	s_add_u32 s12, s12, 0x20000
	s_addc_u32 s13, s13, 0
	v_lshl_add_u64 v[36:37], v[34:35], 0, s[12:13]
	v_lshl_add_u64 v[38:39], v[32:33], 0, s[12:13]
	v_lshl_add_u64 v[40:41], v[30:31], 0, s[12:13]
	v_lshl_add_u64 v[42:43], v[28:29], 0, s[12:13]
	v_lshl_add_u64 v[54:55], v[6:7], 0, s[12:13]
	v_lshl_add_u64 v[56:57], v[4:5], 0, s[12:13]
	v_lshl_add_u64 v[58:59], v[2:3], 0, s[12:13]
	v_lshl_add_u64 v[60:61], v[0:1], 0, s[12:13]
	global_load_dword v78, v[36:37], off nt
	global_load_dword v79, v[38:39], off nt
	global_load_dword v80, v[40:41], off nt
	global_load_dword v81, v[42:43], off nt
	global_load_dword v82, v[54:55], off nt
	global_load_dword v83, v[56:57], off nt
	global_load_dword v84, v[58:59], off nt
	global_load_dword v85, v[60:61], off nt
	s_add_u32 s12, s12, 0x20000
	s_addc_u32 s13, s13, 0
	v_lshl_add_u64 v[36:37], v[34:35], 0, s[12:13]
	v_lshl_add_u64 v[38:39], v[32:33], 0, s[12:13]
	v_lshl_add_u64 v[40:41], v[30:31], 0, s[12:13]
	v_lshl_add_u64 v[42:43], v[28:29], 0, s[12:13]
	v_lshl_add_u64 v[54:55], v[6:7], 0, s[12:13]
	v_lshl_add_u64 v[56:57], v[4:5], 0, s[12:13]
	v_lshl_add_u64 v[58:59], v[2:3], 0, s[12:13]
	v_lshl_add_u64 v[60:61], v[0:1], 0, s[12:13]
	global_load_dword v86, v[36:37], off nt
	global_load_dword v87, v[38:39], off nt
	global_load_dword v88, v[40:41], off nt
	global_load_dword v89, v[42:43], off nt
	global_load_dword v90, v[54:55], off nt
	global_load_dword v91, v[56:57], off nt
	global_load_dword v92, v[58:59], off nt
	global_load_dword v93, v[60:61], off nt
	s_add_u32 s12, s12, 0x20000
	s_addc_u32 s13, s13, 0
	v_lshl_add_u64 v[36:37], v[34:35], 0, s[12:13]
	v_lshl_add_u64 v[38:39], v[32:33], 0, s[12:13]
	v_lshl_add_u64 v[40:41], v[30:31], 0, s[12:13]
	v_lshl_add_u64 v[42:43], v[28:29], 0, s[12:13]
	v_lshl_add_u64 v[54:55], v[6:7], 0, s[12:13]
	v_lshl_add_u64 v[56:57], v[4:5], 0, s[12:13]
	v_lshl_add_u64 v[58:59], v[2:3], 0, s[12:13]
	v_lshl_add_u64 v[60:61], v[0:1], 0, s[12:13]
	global_load_dword v94, v[36:37], off nt
	global_load_dword v95, v[38:39], off nt
	global_load_dword v96, v[40:41], off nt
	global_load_dword v97, v[42:43], off nt
	global_load_dword v98, v[54:55], off nt
	global_load_dword v99, v[56:57], off nt
	global_load_dword v100, v[58:59], off nt
	global_load_dword v101, v[60:61], off nt
	s_add_u32 s12, s12, 0x20000
	s_addc_u32 s13, s13, 0
	v_add_u32_e32 v54, 0x400, v14
	s_waitcnt vmcnt(30)
	ds_write2_b32 v14, v70, v71 offset1:66
	s_waitcnt vmcnt(28)
	ds_write2_b32 v14, v72, v73 offset0:132 offset1:198
	s_waitcnt vmcnt(26)
	ds_write2_b32 v54, v74, v75 offset0:8 offset1:74
	s_waitcnt vmcnt(24)
	ds_write2_b32 v54, v76, v77 offset0:140 offset1:206
	v_add_u32_e32 v14, 0x840, v14
	v_add_u32_e32 v54, 0x400, v14
	s_waitcnt vmcnt(22)
	ds_write2_b32 v14, v78, v79 offset1:66
	s_waitcnt vmcnt(20)
	ds_write2_b32 v14, v80, v81 offset0:132 offset1:198
	s_waitcnt vmcnt(18)
	ds_write2_b32 v54, v82, v83 offset0:8 offset1:74
	s_waitcnt vmcnt(16)
	ds_write2_b32 v54, v84, v85 offset0:140 offset1:206
	v_add_u32_e32 v14, 0x840, v14
	v_add_u32_e32 v54, 0x400, v14
	s_waitcnt vmcnt(14)
	ds_write2_b32 v14, v86, v87 offset1:66
	s_waitcnt vmcnt(12)
	ds_write2_b32 v14, v88, v89 offset0:132 offset1:198
	s_waitcnt vmcnt(10)
	ds_write2_b32 v54, v90, v91 offset0:8 offset1:74
	s_waitcnt vmcnt(8)
	ds_write2_b32 v54, v92, v93 offset0:140 offset1:206
	v_add_u32_e32 v14, 0x840, v14
	v_add_u32_e32 v54, 0x400, v14
	s_waitcnt vmcnt(6)
	ds_write2_b32 v14, v94, v95 offset1:66
	s_waitcnt vmcnt(4)
	ds_write2_b32 v14, v96, v97 offset0:132 offset1:198
	s_waitcnt vmcnt(2)
	ds_write2_b32 v54, v98, v99 offset0:8 offset1:74
	s_waitcnt vmcnt(0)
	ds_write2_b32 v54, v100, v101 offset0:140 offset1:206
	v_add_u32_e32 v14, 0x840, v14
	s_cmp_lg_u32 s12, 0x80000
	s_waitcnt lgkmcnt(0)
	ds_read2_b32 v[4:5], v11 offset1:8
	ds_read2_b32 v[28:29], v11 offset0:33 offset1:41
	ds_read2_b32 v[30:31], v11 offset0:66 offset1:74
	ds_read2_b32 v[32:33], v11 offset0:99 offset1:107
	ds_read2_b32 v[34:35], v11 offset0:132 offset1:140
	s_waitcnt lgkmcnt(4)
	v_bfe_u32 v0, v4, 16, 1
	v_add3_u32 v0, v4, v0, s52
	s_waitcnt lgkmcnt(3)
	v_bfe_u32 v1, v28, 16, 1
	v_lshrrev_b32_e32 v0, 16, v0
	v_add3_u32 v1, v28, v1, s52
	ds_read2_b32 v[36:37], v11 offset0:165 offset1:173
	v_and_or_b32 v0, v1, s53, v0
	s_waitcnt lgkmcnt(3)
	v_bfe_u32 v1, v30, 16, 1
	v_add3_u32 v1, v30, v1, s52
	s_waitcnt lgkmcnt(2)
	v_bfe_u32 v2, v32, 16, 1
	ds_read2_b32 v[38:39], v11 offset0:198 offset1:206
	v_lshrrev_b32_e32 v1, 16, v1
	v_add3_u32 v2, v32, v2, s52
	ds_read2_b32 v[40:41], v11 offset0:231 offset1:239
	s_lshl_b32 s12, s56, 5
	v_and_or_b32 v1, v2, s53, v1
	s_waitcnt lgkmcnt(3)
	v_bfe_u32 v2, v34, 16, 1
	s_and_b32 s17, s12, 0x7e0
	s_mul_i32 s12, s0, 0x1600000
	v_add3_u32 v2, v34, v2, s52
	s_waitcnt lgkmcnt(2)
	v_bfe_u32 v3, v36, 16, 1
	s_add_u32 s12, s33, s12
	v_lshrrev_b32_e32 v2, 16, v2
	v_add3_u32 v3, v36, v3, s52
	s_addc_u32 s13, s44, 0
	s_lshl_b32 s16, s16, 1
	v_and_or_b32 v2, v3, s53, v2
	s_waitcnt lgkmcnt(1)
	v_bfe_u32 v3, v38, 16, 1
	s_add_u32 s12, s12, s16
	v_add3_u32 v3, v38, v3, s52
	s_waitcnt lgkmcnt(0)
	v_bfe_u32 v4, v40, 16, 1
	s_addc_u32 s13, s13, 0
	v_lshlrev_b32_e32 v14, 1, v12
	v_lshrrev_b32_e32 v3, 16, v3
	v_add3_u32 v4, v40, v4, s52
	v_lshl_add_u64 v[6:7], s[12:13], 0, v[14:15]
	v_and_or_b32 v3, v4, s53, v3
	v_add_u32_e32 v4, s17, v9
	v_mad_i64_i32 v[42:43], s[12:13], v4, s49, v[6:7]
	global_store_dwordx4 v[42:43], v[0:3], off nt
	v_bfe_u32 v4, v41, 16, 1
	v_add3_u32 v4, v41, v4, s52
	v_bfe_u32 v0, v5, 16, 1
	v_add3_u32 v0, v5, v0, s52
	v_bfe_u32 v1, v29, 16, 1
	v_lshrrev_b32_e32 v0, 16, v0
	v_add3_u32 v1, v29, v1, s52
	v_and_or_b32 v0, v1, s53, v0
	v_bfe_u32 v1, v31, 16, 1
	v_add3_u32 v1, v31, v1, s52
	v_bfe_u32 v2, v33, 16, 1
	v_lshrrev_b32_e32 v1, 16, v1
	v_add3_u32 v2, v33, v2, s52
	v_and_or_b32 v1, v2, s53, v1
	v_bfe_u32 v2, v35, 16, 1
	v_add3_u32 v2, v35, v2, s52
	v_bfe_u32 v3, v37, 16, 1
	v_lshrrev_b32_e32 v2, 16, v2
	v_add3_u32 v3, v37, v3, s52
	v_and_or_b32 v2, v3, s53, v2
	v_bfe_u32 v3, v39, 16, 1
	v_add3_u32 v3, v39, v3, s52
	v_lshrrev_b32_e32 v3, 16, v3
	v_add_u32_e32 v14, s17, v13
	v_and_or_b32 v3, v4, s53, v3
	ds_read2_b32 v[4:5], v11 offset0:16 offset1:24
	v_mad_i64_i32 v[28:29], s[12:13], v14, s49, v[6:7]
	global_store_dwordx4 v[28:29], v[0:3], off nt
	ds_read2_b32 v[28:29], v11 offset0:49 offset1:57
	ds_read2_b32 v[30:31], v11 offset0:82 offset1:90
	ds_read2_b32 v[32:33], v11 offset0:115 offset1:123
	s_waitcnt lgkmcnt(3)
	v_bfe_u32 v0, v4, 16, 1
	v_add3_u32 v0, v4, v0, s52
	s_waitcnt lgkmcnt(2)
	v_bfe_u32 v1, v28, 16, 1
	ds_read2_b32 v[34:35], v11 offset0:148 offset1:156
	v_lshrrev_b32_e32 v0, 16, v0
	v_add3_u32 v1, v28, v1, s52
	ds_read2_b32 v[36:37], v11 offset0:181 offset1:189
	v_and_or_b32 v0, v1, s53, v0
	s_waitcnt lgkmcnt(3)
	v_bfe_u32 v1, v30, 16, 1
	v_add3_u32 v1, v30, v1, s52
	s_waitcnt lgkmcnt(2)
	v_bfe_u32 v2, v32, 16, 1
	ds_read2_b32 v[38:39], v11 offset0:214 offset1:222
	v_lshrrev_b32_e32 v1, 16, v1
	v_add3_u32 v2, v32, v2, s52
	ds_read2_b32 v[40:41], v11 offset0:247 offset1:255
	v_and_or_b32 v1, v2, s53, v1
	s_waitcnt lgkmcnt(3)
	v_bfe_u32 v2, v34, 16, 1
	v_add3_u32 v2, v34, v2, s52
	s_waitcnt lgkmcnt(2)
	v_bfe_u32 v3, v36, 16, 1
	v_lshrrev_b32_e32 v2, 16, v2
	v_add3_u32 v3, v36, v3, s52
	v_and_or_b32 v2, v3, s53, v2
	s_waitcnt lgkmcnt(1)
	v_bfe_u32 v3, v38, 16, 1
	v_add3_u32 v3, v38, v3, s52
	s_waitcnt lgkmcnt(0)
	v_bfe_u32 v4, v40, 16, 1
	v_lshrrev_b32_e32 v3, 16, v3
	v_add3_u32 v4, v40, v4, s52
	v_and_or_b32 v3, v4, s53, v3
	v_add_u32_e32 v4, s17, v44
	v_mad_i64_i32 v[42:43], s[12:13], v4, s49, v[6:7]
	global_store_dwordx4 v[42:43], v[0:3], off nt
	v_bfe_u32 v4, v41, 16, 1
	v_add3_u32 v4, v41, v4, s52
	v_bfe_u32 v0, v5, 16, 1
	v_add3_u32 v0, v5, v0, s52
	v_bfe_u32 v1, v29, 16, 1
	v_lshrrev_b32_e32 v0, 16, v0
	v_add3_u32 v1, v29, v1, s52
	v_and_or_b32 v0, v1, s53, v0
	v_bfe_u32 v1, v31, 16, 1
	v_add3_u32 v1, v31, v1, s52
	v_bfe_u32 v2, v33, 16, 1
	v_lshrrev_b32_e32 v1, 16, v1
	v_add3_u32 v2, v33, v2, s52
	v_and_or_b32 v1, v2, s53, v1
	v_bfe_u32 v2, v35, 16, 1
	v_add3_u32 v2, v35, v2, s52
	v_bfe_u32 v3, v37, 16, 1
	v_lshrrev_b32_e32 v2, 16, v2
	v_add3_u32 v3, v37, v3, s52
	v_and_or_b32 v2, v3, s53, v2
	v_bfe_u32 v3, v39, 16, 1
	v_add3_u32 v3, v39, v3, s52
	v_lshrrev_b32_e32 v3, 16, v3
	v_and_or_b32 v3, v4, s53, v3
	v_add_u32_e32 v4, s17, v45
	v_mad_i64_i32 v[4:5], s[12:13], v4, s49, v[6:7]
	global_store_dwordx4 v[4:5], v[0:3], off nt
	s_waitcnt lgkmcnt(0)

.LBB0_54:
	v_lshl_add_u64 v[54:55], v[42:43], 0, s[30:31]
	v_lshl_add_u64 v[56:57], v[40:41], 0, s[30:31]
	v_lshl_add_u64 v[58:59], v[38:39], 0, s[30:31]
	v_lshl_add_u64 v[60:61], v[36:37], 0, s[30:31]
	v_lshl_add_u64 v[62:63], v[34:35], 0, s[30:31]
	v_lshl_add_u64 v[64:65], v[32:33], 0, s[30:31]
	v_lshl_add_u64 v[66:67], v[30:31], 0, s[30:31]
	v_lshl_add_u64 v[68:69], v[28:29], 0, s[30:31]
	global_load_dword v70, v[54:55], off nt
	global_load_dword v71, v[56:57], off nt
	global_load_dword v72, v[58:59], off nt
	global_load_dword v73, v[60:61], off nt
	global_load_dword v74, v[62:63], off nt
	global_load_dword v75, v[64:65], off nt
	global_load_dword v76, v[66:67], off nt
	global_load_dword v77, v[68:69], off nt
	s_add_u32 s30, s30, 0x58000
	s_addc_u32 s31, s31, 0
	v_lshl_add_u64 v[54:55], v[42:43], 0, s[30:31]
	v_lshl_add_u64 v[56:57], v[40:41], 0, s[30:31]
	v_lshl_add_u64 v[58:59], v[38:39], 0, s[30:31]
	v_lshl_add_u64 v[60:61], v[36:37], 0, s[30:31]
	v_lshl_add_u64 v[62:63], v[34:35], 0, s[30:31]
	v_lshl_add_u64 v[64:65], v[32:33], 0, s[30:31]
	v_lshl_add_u64 v[66:67], v[30:31], 0, s[30:31]
	v_lshl_add_u64 v[68:69], v[28:29], 0, s[30:31]
	global_load_dword v78, v[54:55], off nt
	global_load_dword v79, v[56:57], off nt
	global_load_dword v80, v[58:59], off nt
	global_load_dword v81, v[60:61], off nt
	global_load_dword v82, v[62:63], off nt
	global_load_dword v83, v[64:65], off nt
	global_load_dword v84, v[66:67], off nt
	global_load_dword v85, v[68:69], off nt
	s_add_u32 s30, s30, 0x58000
	s_addc_u32 s31, s31, 0
	v_lshl_add_u64 v[54:55], v[42:43], 0, s[30:31]
	v_lshl_add_u64 v[56:57], v[40:41], 0, s[30:31]
	v_lshl_add_u64 v[58:59], v[38:39], 0, s[30:31]
	v_lshl_add_u64 v[60:61], v[36:37], 0, s[30:31]
	v_lshl_add_u64 v[62:63], v[34:35], 0, s[30:31]
	v_lshl_add_u64 v[64:65], v[32:33], 0, s[30:31]
	v_lshl_add_u64 v[66:67], v[30:31], 0, s[30:31]
	v_lshl_add_u64 v[68:69], v[28:29], 0, s[30:31]
	global_load_dword v86, v[54:55], off nt
	global_load_dword v87, v[56:57], off nt
	global_load_dword v88, v[58:59], off nt
	global_load_dword v89, v[60:61], off nt
	global_load_dword v90, v[62:63], off nt
	global_load_dword v91, v[64:65], off nt
	global_load_dword v92, v[66:67], off nt
	global_load_dword v93, v[68:69], off nt
	s_add_u32 s30, s30, 0x58000
	s_addc_u32 s31, s31, 0
	v_lshl_add_u64 v[54:55], v[42:43], 0, s[30:31]
	v_lshl_add_u64 v[56:57], v[40:41], 0, s[30:31]
	v_lshl_add_u64 v[58:59], v[38:39], 0, s[30:31]
	v_lshl_add_u64 v[60:61], v[36:37], 0, s[30:31]
	v_lshl_add_u64 v[62:63], v[34:35], 0, s[30:31]
	v_lshl_add_u64 v[64:65], v[32:33], 0, s[30:31]
	v_lshl_add_u64 v[66:67], v[30:31], 0, s[30:31]
	v_lshl_add_u64 v[68:69], v[28:29], 0, s[30:31]
	global_load_dword v94, v[54:55], off nt
	global_load_dword v95, v[56:57], off nt
	global_load_dword v96, v[58:59], off nt
	global_load_dword v97, v[60:61], off nt
	global_load_dword v98, v[62:63], off nt
	global_load_dword v99, v[64:65], off nt
	global_load_dword v100, v[66:67], off nt
	global_load_dword v101, v[68:69], off nt
	s_add_u32 s30, s30, 0x58000
	s_addc_u32 s31, s31, 0
	v_add_u32_e32 v62, 0x400, v14
	s_waitcnt vmcnt(30)
	ds_write2_b32 v14, v70, v71 offset1:66
	s_waitcnt vmcnt(28)
	ds_write2_b32 v14, v72, v73 offset0:132 offset1:198
	s_waitcnt vmcnt(26)
	ds_write2_b32 v62, v74, v75 offset0:8 offset1:74
	s_waitcnt vmcnt(24)
	ds_write2_b32 v62, v76, v77 offset0:140 offset1:206
	v_add_u32_e32 v14, 0x840, v14
	v_add_u32_e32 v62, 0x400, v14
	s_waitcnt vmcnt(22)
	ds_write2_b32 v14, v78, v79 offset1:66
	s_waitcnt vmcnt(20)
	ds_write2_b32 v14, v80, v81 offset0:132 offset1:198
	s_waitcnt vmcnt(18)
	ds_write2_b32 v62, v82, v83 offset0:8 offset1:74
	s_waitcnt vmcnt(16)
	ds_write2_b32 v62, v84, v85 offset0:140 offset1:206
	v_add_u32_e32 v14, 0x840, v14
	v_add_u32_e32 v62, 0x400, v14
	s_waitcnt vmcnt(14)
	ds_write2_b32 v14, v86, v87 offset1:66
	s_waitcnt vmcnt(12)
	ds_write2_b32 v14, v88, v89 offset0:132 offset1:198
	s_waitcnt vmcnt(10)
	ds_write2_b32 v62, v90, v91 offset0:8 offset1:74
	s_waitcnt vmcnt(8)
	ds_write2_b32 v62, v92, v93 offset0:140 offset1:206
	v_add_u32_e32 v14, 0x840, v14
	v_add_u32_e32 v62, 0x400, v14
	s_waitcnt vmcnt(6)
	ds_write2_b32 v14, v94, v95 offset1:66
	s_waitcnt vmcnt(4)
	ds_write2_b32 v14, v96, v97 offset0:132 offset1:198
	s_waitcnt vmcnt(2)
	ds_write2_b32 v62, v98, v99 offset0:8 offset1:74
	s_waitcnt vmcnt(0)
	ds_write2_b32 v62, v100, v101 offset0:140 offset1:206
	v_add_u32_e32 v14, 0x840, v14
	s_cmp_lg_u32 s30, 0x160000
	s_waitcnt lgkmcnt(0)
	ds_read2_b32 v[32:33], v11 offset1:8
	ds_read2_b32 v[34:35], v11 offset0:33 offset1:41
	ds_read2_b32 v[38:39], v11 offset0:66 offset1:74
	ds_read2_b32 v[40:41], v11 offset0:99 offset1:107
	s_and_b32 s28, s28, 0x60
	ds_read2_b32 v[42:43], v11 offset0:132 offset1:140
	ds_read2_b32 v[54:55], v11 offset0:165 offset1:173
	ds_read2_b32 v[56:57], v11 offset0:198 offset1:206
	ds_read2_b32 v[58:59], v11 offset0:231 offset1:239
	s_and_b64 s[12:13], s[12:13], exec
	s_cselect_b32 s12, 0x80, 0
	s_lshl_b32 s13, s34, 6
	s_or_b32 s12, s28, s12
	s_waitcnt lgkmcnt(7)
	v_mov_b32_e32 v28, v32
	s_waitcnt lgkmcnt(6)
	v_mov_b32_e32 v29, v34
	s_waitcnt lgkmcnt(5)
	v_mov_b32_e32 v30, v38
	s_waitcnt lgkmcnt(4)
	v_mov_b32_e32 v31, v40
	s_add_u32 s0, s45, s0
	v_pk_mul_f32 v[28:29], v[4:5], v[28:29]
	v_pk_mul_f32 v[30:31], v[6:7], v[30:31]
	s_addc_u32 s28, s46, 0
	s_and_b32 s13, s13, 0xffffff00
	v_cvt_pk_f16_f32 v28, v28, v29
	v_cvt_pk_f16_f32 v29, v30, v31
	s_waitcnt lgkmcnt(3)
	v_mov_b32_e32 v30, v42
	s_waitcnt lgkmcnt(2)
	v_mov_b32_e32 v31, v54
	s_waitcnt lgkmcnt(1)
	v_mov_b32_e32 v60, v56
	s_waitcnt lgkmcnt(0)
	v_mov_b32_e32 v61, v58
	s_or_b32 s29, s12, s13
	s_lshl_b64 s[12:13], s[16:17], 1
	v_pk_mul_f32 v[30:31], v[0:1], v[30:31]
	v_pk_mul_f32 v[60:61], v[2:3], v[60:61]
	s_add_u32 s12, s0, s12
	v_cvt_pk_f16_f32 v30, v30, v31
	v_cvt_pk_f16_f32 v31, v60, v61
	v_add_u32_e32 v60, s29, v9
	s_addc_u32 s13, s28, s13
	v_lshlrev_b32_e32 v14, 1, v12
	v_ashrrev_i32_e32 v61, 31, v60
	v_lshl_add_u64 v[36:37], s[12:13], 0, v[14:15]
	v_lshlrev_b64 v[60:61], 12, v[60:61]
	v_lshl_add_u64 v[60:61], v[36:37], 0, v[60:61]
	v_mov_b32_e32 v34, v33
	v_mov_b32_e32 v40, v39
	global_store_dwordx4 v[60:61], v[28:31], off nt
	v_mov_b32_e32 v54, v43
	v_mov_b32_e32 v58, v57
	v_pk_mul_f32 v[28:29], v[4:5], v[34:35]
	v_pk_mul_f32 v[30:31], v[6:7], v[40:41]
	v_cvt_pk_f16_f32 v28, v28, v29
	v_cvt_pk_f16_f32 v29, v30, v31
	v_pk_mul_f32 v[30:31], v[0:1], v[54:55]
	v_pk_mul_f32 v[32:33], v[2:3], v[58:59]
	v_cvt_pk_f16_f32 v30, v30, v31
	v_cvt_pk_f16_f32 v31, v32, v33
	v_add_u32_e32 v32, s29, v13
	v_ashrrev_i32_e32 v33, 31, v32
	v_lshlrev_b64 v[32:33], 12, v[32:33]
	v_lshl_add_u64 v[32:33], v[36:37], 0, v[32:33]
	ds_read2_b32 v[34:35], v11 offset0:16 offset1:24
	ds_read2_b32 v[38:39], v11 offset0:49 offset1:57
	global_store_dwordx4 v[32:33], v[28:31], off nt
	ds_read2_b32 v[32:33], v11 offset0:82 offset1:90
	ds_read2_b32 v[40:41], v11 offset0:115 offset1:123
	ds_read2_b32 v[42:43], v11 offset0:148 offset1:156
	ds_read2_b32 v[54:55], v11 offset0:181 offset1:189
	ds_read2_b32 v[56:57], v11 offset0:214 offset1:222
	ds_read2_b32 v[58:59], v11 offset0:247 offset1:255
	s_waitcnt lgkmcnt(7)
	v_mov_b32_e32 v28, v34
	s_waitcnt lgkmcnt(6)
	v_mov_b32_e32 v29, v38
	s_waitcnt lgkmcnt(5)
	v_mov_b32_e32 v30, v32
	s_waitcnt lgkmcnt(4)
	v_mov_b32_e32 v31, v40
	v_pk_mul_f32 v[28:29], v[4:5], v[28:29]
	v_pk_mul_f32 v[30:31], v[6:7], v[30:31]
	v_cvt_pk_f16_f32 v28, v28, v29
	v_cvt_pk_f16_f32 v29, v30, v31
	s_waitcnt lgkmcnt(3)
	v_mov_b32_e32 v30, v42
	s_waitcnt lgkmcnt(2)
	v_mov_b32_e32 v31, v54
	v_mov_b32_e32 v38, v35
	v_mov_b32_e32 v40, v33
	v_mov_b32_e32 v54, v43
	v_pk_mul_f32 v[30:31], v[0:1], v[30:31]
	s_waitcnt lgkmcnt(1)
	v_mov_b32_e32 v60, v56
	s_waitcnt lgkmcnt(0)
	v_mov_b32_e32 v61, v58
	v_pk_mul_f32 v[4:5], v[4:5], v[38:39]
	v_pk_mul_f32 v[6:7], v[6:7], v[40:41]
	v_pk_mul_f32 v[0:1], v[0:1], v[54:55]
	v_mov_b32_e32 v58, v57
	v_pk_mul_f32 v[60:61], v[2:3], v[60:61]
	v_cvt_pk_f16_f32 v4, v4, v5
	v_cvt_pk_f16_f32 v5, v6, v7
	v_cvt_pk_f16_f32 v6, v0, v1
	v_pk_mul_f32 v[0:1], v[2:3], v[58:59]
	v_cvt_pk_f16_f32 v30, v30, v31
	v_cvt_pk_f16_f32 v31, v60, v61
	v_add_u32_e32 v60, s29, v44
	v_cvt_pk_f16_f32 v7, v0, v1
	v_add_u32_e32 v0, s29, v45
	v_ashrrev_i32_e32 v61, 31, v60
	v_ashrrev_i32_e32 v1, 31, v0
	v_lshlrev_b64 v[60:61], 12, v[60:61]
	v_lshlrev_b64 v[0:1], 12, v[0:1]
	v_lshl_add_u64 v[60:61], v[36:37], 0, v[60:61]
	v_lshl_add_u64 v[0:1], v[36:37], 0, v[0:1]
	global_store_dwordx4 v[60:61], v[28:31], off nt
	global_store_dwordx4 v[0:1], v[4:7], off nt
	s_waitcnt lgkmcnt(0)
	s_branch .LBB0_15
